# layer-1 input-projection weight conversion moved from the input-projection riding slot to the first gate/up riding slot of layer 0 (pair units only remain in the former)
# baseline (speedup 1.0000x reference)
.Lcva_done:
	v_readlane_b32 s0, v253, 43
	s_lshl_b32 s0, s0, 3
	v_readlane_b32 s1, v253, 45
	s_add_i32 s0, s0, s1
	s_add_i32 s4, s0, 0x1200
	s_movk_i32 s24, 0x400
	s_movk_i32 s25, 0x1a80
	v_readlane_b32 s0, v253, 45
	s_mulk_i32 s0, 0x4200
	s_add_i32 s0, s97, s0
	v_readlane_b32 s22, v253, 41
	v_readlane_b32 s23, v253, 42
	v_readlane_b32 s6, v252, 1
	v_readlane_b32 s7, v252, 2
	s_load_dwordx4 s[8:11], s[6:7], 0x48
	s_load_dwordx4 s[12:15], s[6:7], 0x58
	s_load_dwordx2 s[20:21], s[6:7], 0xb0
	v_lshlrev_b32_e32 v0, 1, v238
	v_and_b32_e32 v8, 3, v237
	v_and_or_b32 v8, v0, 24, v8
	v_lshrrev_b32_e32 v9, 2, v237
	v_and_or_b32 v9, v9, 4, v8
	v_lshlrev_b32_e32 v8, 2, v8
	v_lshlrev_b32_e32 v9, 2, v9
	v_lshrrev_b32_e32 v7, 5, v238
	v_lshrrev_b32_e32 v12, 3, v238
	v_lshlrev_b32_e32 v11, 3, v238
	v_and_b32_e32 v11, 56, v11
	v_lshlrev_b32_e32 v10, 1, v11
	v_mul_u32_u24_e32 v3, 0x1600, v12
	v_add_u32_e32 v3, v3, v10
	v_lshl_add_u32 v4, v12, 11, v10
	v_and_b32_e32 v10, 31, v237
	v_lshlrev_b32_e32 v10, 2, v10
	v_mul_u32_u24_e32 v2, 0x84, v7
	v_add3_u32 v13, s0, v10, v2
	v_add_u32_e32 v14, 0x400, v13
	v_add_u32_e32 v15, 0x800, v13
	v_add_u32_e32 v16, 0xc00, v13
	v_add_u32_e32 v17, 0x1000, v13
	v_add_u32_e32 v18, 0x1400, v13
	v_add_u32_e32 v19, 0x1800, v13
	v_add_u32_e32 v20, 0x1c00, v13
	v_mul_u32_u24_e32 v10, 0x84, v11
	v_lshlrev_b32_e32 v2, 2, v12
	v_add3_u32 v21, s0, v10, v2
	v_and_b32_e32 v10, 16, v237
	v_cmp_eq_u32_e32 vcc, 0, v10
	s_waitcnt lgkmcnt(0)
	v_mov_b32_e32 v10, s10
	v_mov_b32_e32 v11, s8
	v_cndmask_b32_e32 v104, v10, v11, vcc
	v_mov_b32_e32 v10, s11
	v_mov_b32_e32 v11, s9
	v_cndmask_b32_e32 v105, v10, v11, vcc
	v_mov_b32_e32 v11, v1
	v_mul_u32_u24_e32 v10, 0x2c00, v7
	v_add_u32_e32 v10, v10, v8
	v_lshl_add_u64 v[104:105], v[104:105], 0, v[10:11]
	v_mul_u32_u24_e32 v10, 0x2400, v7
	v_add_u32_e32 v10, v10, v9
	v_lshl_add_u64 v[106:107], s[14:15], 0, v[10:11]
	v_lshl_add_u32 v10, v7, 12, v9
	v_lshl_add_u64 v[108:109], s[12:13], 0, v[10:11]
	v_lshl_add_u64 v[110:111], s[20:21], 0, v[10:11]
	s_cmpk_lt_u32 s4, 0x1600
	s_cbranch_scc0 .Lcvx_ngu1
	s_cmpk_gt_u32 s4, 0xaff
	s_cselect_b32 s5, 1, 0
	s_mul_i32 s6, s5, 0xb00
	s_sub_i32 s6, s4, s6
	s_mul_i32 s7, s6, 0xba3
	s_lshr_b32 s7, s7, 19
	s_mul_i32 s8, s7, 0xb0
	s_sub_i32 s6, s6, s8
	s_lshr_b32 s8, s6, 3
	s_lshl_b32 s8, s8, 7
	s_and_b32 s9, s6, 3
	s_lshl_b32 s9, s9, 5
	s_add_i32 s8, s8, s9
	s_bfe_u32 s9, s6, 0x10002
	s_lshl_b32 s9, s9, 2
	s_add_i32 s8, s8, s9
	s_lshl_b32 s8, s8, 2
	s_mul_i32 s9, s5, 0xb00000
	s_add_u32 s8, s8, s9
	s_add_u32 s8, s8, 0x1600000
	s_mul_i32 s9, s7, 0xb0000
	s_add_u32 s10, s8, s9
	s_mov_b32 s11, 0
	v_lshl_add_u64 v[22:23], v[104:105], 0, s[10:11]
	s_mov_b64 s[26:27], 0x5800
	s_mul_i32 s8, s5, 0xf80000
	s_lshl_b32 s9, s6, 16
	s_add_u32 s8, s8, s9
	s_lshl_b32 s9, s7, 7
	s_add_u32 s8, s8, s9
	s_add_u32 s8, s8, 0x3780000
	s_add_u32 s12, s22, s8
	s_addc_u32 s13, s23, 0
	s_mov_b32 s14, 0x4000
	v_mov_b32_e32 v5, v4
	s_branch .Lcvx_d1
.Lcvx_ngu1:
	s_cmpk_lt_u32 s4, 0x1a80
	s_cbranch_scc0 .Lcvx_nin1
	s_add_i32 s6, s4, 0xffffea00
	s_mul_i32 s7, s6, 0x38f
	s_lshr_b32 s7, s7, 16
	s_mul_i32 s8, s7, 0x48
	s_sub_i32 s6, s6, s8
	s_lshr_b32 s8, s6, 3
	s_lshl_b32 s8, s8, 8
	s_and_b32 s9, s6, 3
	s_lshl_b32 s9, s9, 6
	s_add_i32 s8, s8, s9
	s_bfe_u32 s9, s6, 0x10002
	s_lshl_b32 s9, s9, 5
	s_add_i32 s8, s8, s9
	s_lshl_b32 s8, s8, 2
	s_add_u32 s8, s8, 0x900000
	s_mul_i32 s9, s7, 0x90000
	s_add_u32 s10, s8, s9
	s_mov_b32 s11, 0
	v_lshl_add_u64 v[22:23], v[106:107], 0, s[10:11]
	s_mov_b64 s[26:27], 0x4800
	s_lshl_b32 s8, s6, 16
	s_lshl_b32 s9, s7, 7
	s_add_u32 s8, s8, s9
	s_add_u32 s8, s8, 0x4280000
	s_add_u32 s12, s22, s8
	s_addc_u32 s13, s23, 0
	s_mov_b32 s14, 0x4000
	v_mov_b32_e32 v5, v4
	s_branch .Lcvx_d1
.Lcvx_nin1:
	s_cmpk_lt_u32 s4, 0x2580
	s_cbranch_scc0 .Lcvx_o1
	s_cmpk_gt_u32 s4, 0x1fff
	s_cselect_b32 s5, 1, 0
	s_mul_i32 s6, s5, 0x580
	s_sub_i32 s6, s4, s6
	s_addk_i32 s6, 0xe580
	s_lshr_b32 s7, s6, 5
	s_and_b32 s6, s6, 31
	s_mul_i32 s8, s5, 0xb00000
	s_add_u32 s8, s8, 0x1600000
	s_lshl_b32 s9, s6, 7
	s_add_u32 s8, s8, s9
	s_lshl_b32 s9, s7, 18
	s_add_u32 s10, s8, s9
	s_mov_b32 s11, 0
	v_lshl_add_u64 v[22:23], v[108:109], 0, s[10:11]
	s_mov_b64 s[26:27], 0x2000
	s_mul_i32 s8, s5, 0x580000
	s_mul_i32 s9, s6, 0x2c000
	s_add_u32 s8, s8, s9
	s_lshl_b32 s9, s7, 7
	s_add_u32 s8, s8, s9
	s_add_u32 s8, s8, 0x5200000
	s_add_u32 s12, s22, s8
	s_addc_u32 s13, s23, 0
	s_mov_b32 s14, 0xb000
	v_mov_b32_e32 v5, v3
	s_branch .Lcvx_d1
.Lcvx_o1:
	s_add_i32 s6, s4, 0xffffda80
	s_lshr_b32 s7, s6, 5
	s_and_b32 s6, s6, 31
	s_lshl_b32 s8, s6, 7
	s_lshl_b32 s9, s7, 18
	s_add_u32 s10, s8, s9
	s_add_u32 s10, s10, 0x400000
	s_mov_b32 s11, 0
	v_lshl_add_u64 v[22:23], v[110:111], 0, s[10:11]
	s_mov_b64 s[26:27], 0x2000
	s_lshl_b32 s8, s6, 16
	s_lshl_b32 s9, s7, 7
	s_add_u32 s8, s8, s9
	s_add_u32 s8, s8, 0x5d00000
	s_add_u32 s12, s22, s8
	s_addc_u32 s13, s23, 0
	s_mov_b32 s14, 0x4000
	v_mov_b32_e32 v5, v4
.Lcvx_d1:
	global_load_dword v24, v[22:23], off nt
	v_lshl_add_u64 v[22:23], v[22:23], 0, s[26:27]
	global_load_dword v25, v[22:23], off nt
	v_lshl_add_u64 v[22:23], v[22:23], 0, s[26:27]
	global_load_dword v26, v[22:23], off nt
	v_lshl_add_u64 v[22:23], v[22:23], 0, s[26:27]
	global_load_dword v27, v[22:23], off nt
	v_lshl_add_u64 v[22:23], v[22:23], 0, s[26:27]
	global_load_dword v28, v[22:23], off nt
	v_lshl_add_u64 v[22:23], v[22:23], 0, s[26:27]
	global_load_dword v29, v[22:23], off nt
	v_lshl_add_u64 v[22:23], v[22:23], 0, s[26:27]
	global_load_dword v30, v[22:23], off nt
	v_lshl_add_u64 v[22:23], v[22:23], 0, s[26:27]
	global_load_dword v31, v[22:23], off nt
	v_lshl_add_u64 v[22:23], v[22:23], 0, s[26:27]
	global_load_dword v32, v[22:23], off nt
	v_lshl_add_u64 v[22:23], v[22:23], 0, s[26:27]
	global_load_dword v33, v[22:23], off nt
	v_lshl_add_u64 v[22:23], v[22:23], 0, s[26:27]
	global_load_dword v34, v[22:23], off nt
	v_lshl_add_u64 v[22:23], v[22:23], 0, s[26:27]
	global_load_dword v35, v[22:23], off nt
	v_lshl_add_u64 v[22:23], v[22:23], 0, s[26:27]
	global_load_dword v36, v[22:23], off nt
	v_lshl_add_u64 v[22:23], v[22:23], 0, s[26:27]
	global_load_dword v37, v[22:23], off nt
	v_lshl_add_u64 v[22:23], v[22:23], 0, s[26:27]
	global_load_dword v38, v[22:23], off nt
	v_lshl_add_u64 v[22:23], v[22:23], 0, s[26:27]
	global_load_dword v39, v[22:23], off nt
	v_lshl_add_u64 v[22:23], v[22:23], 0, s[26:27]
	global_load_dword v40, v[22:23], off nt
	v_lshl_add_u64 v[22:23], v[22:23], 0, s[26:27]
	global_load_dword v41, v[22:23], off nt
	v_lshl_add_u64 v[22:23], v[22:23], 0, s[26:27]
	global_load_dword v42, v[22:23], off nt
	v_lshl_add_u64 v[22:23], v[22:23], 0, s[26:27]
	global_load_dword v43, v[22:23], off nt
	v_lshl_add_u64 v[22:23], v[22:23], 0, s[26:27]
	global_load_dword v44, v[22:23], off nt
	v_lshl_add_u64 v[22:23], v[22:23], 0, s[26:27]
	global_load_dword v45, v[22:23], off nt
	v_lshl_add_u64 v[22:23], v[22:23], 0, s[26:27]
	global_load_dword v46, v[22:23], off nt
	v_lshl_add_u64 v[22:23], v[22:23], 0, s[26:27]
	global_load_dword v47, v[22:23], off nt
	v_lshl_add_u64 v[22:23], v[22:23], 0, s[26:27]
	global_load_dword v48, v[22:23], off nt
	v_lshl_add_u64 v[22:23], v[22:23], 0, s[26:27]
	global_load_dword v49, v[22:23], off nt
	v_lshl_add_u64 v[22:23], v[22:23], 0, s[26:27]
	global_load_dword v50, v[22:23], off nt
	v_lshl_add_u64 v[22:23], v[22:23], 0, s[26:27]
	global_load_dword v51, v[22:23], off nt
	v_lshl_add_u64 v[22:23], v[22:23], 0, s[26:27]
	global_load_dword v52, v[22:23], off nt
	v_lshl_add_u64 v[22:23], v[22:23], 0, s[26:27]
	global_load_dword v53, v[22:23], off nt
	v_lshl_add_u64 v[22:23], v[22:23], 0, s[26:27]
	global_load_dword v54, v[22:23], off nt
	v_lshl_add_u64 v[22:23], v[22:23], 0, s[26:27]
	global_load_dword v55, v[22:23], off nt
	s_waitcnt vmcnt(0)
.Lcvx_top:
	s_mov_b64 s[20:21], s[12:13]
	s_mov_b32 s15, s14
	v_mov_b32_e32 v6, v5
	ds_write2_b32 v13, v24, v25 offset0:0 offset1:66
	ds_write2_b32 v13, v26, v27 offset0:132 offset1:198
	ds_write2_b32 v14, v28, v29 offset0:8 offset1:74
	ds_write2_b32 v14, v30, v31 offset0:140 offset1:206
	ds_write2_b32 v15, v32, v33 offset0:16 offset1:82
	ds_write2_b32 v15, v34, v35 offset0:148 offset1:214
	ds_write2_b32 v16, v36, v37 offset0:24 offset1:90
	ds_write2_b32 v16, v38, v39 offset0:156 offset1:222
	ds_write2_b32 v17, v40, v41 offset0:32 offset1:98
	ds_write2_b32 v17, v42, v43 offset0:164 offset1:230
	ds_write2_b32 v18, v44, v45 offset0:40 offset1:106
	ds_write2_b32 v18, v46, v47 offset0:172 offset1:238
	ds_write2_b32 v19, v48, v49 offset0:48 offset1:114
	ds_write2_b32 v19, v50, v51 offset0:180 offset1:246
	ds_write2_b32 v20, v52, v53 offset0:56 offset1:122
	ds_write2_b32 v20, v54, v55 offset0:188 offset1:254
	s_add_i32 s4, s4, s24
	s_cmp_lt_u32 s4, s25
	s_cbranch_scc0 .Lcvx_noload
	s_cmpk_lt_u32 s4, 0x1600
	s_cbranch_scc0 .Lcvx_ngu2
	s_cmpk_gt_u32 s4, 0xaff
	s_cselect_b32 s5, 1, 0
	s_mul_i32 s6, s5, 0xb00
	s_sub_i32 s6, s4, s6
	s_mul_i32 s7, s6, 0xba3
	s_lshr_b32 s7, s7, 19
	s_mul_i32 s8, s7, 0xb0
	s_sub_i32 s6, s6, s8
	s_lshr_b32 s8, s6, 3
	s_lshl_b32 s8, s8, 7
	s_and_b32 s9, s6, 3
	s_lshl_b32 s9, s9, 5
	s_add_i32 s8, s8, s9
	s_bfe_u32 s9, s6, 0x10002
	s_lshl_b32 s9, s9, 2
	s_add_i32 s8, s8, s9
	s_lshl_b32 s8, s8, 2
	s_mul_i32 s9, s5, 0xb00000
	s_add_u32 s8, s8, s9
	s_add_u32 s8, s8, 0x1600000
	s_mul_i32 s9, s7, 0xb0000
	s_add_u32 s10, s8, s9
	s_mov_b32 s11, 0
	v_lshl_add_u64 v[22:23], v[104:105], 0, s[10:11]
	s_mov_b64 s[26:27], 0x5800
	s_mul_i32 s8, s5, 0xf80000
	s_lshl_b32 s9, s6, 16
	s_add_u32 s8, s8, s9
	s_lshl_b32 s9, s7, 7
	s_add_u32 s8, s8, s9
	s_add_u32 s8, s8, 0x3780000
	s_add_u32 s12, s22, s8
	s_addc_u32 s13, s23, 0
	s_mov_b32 s14, 0x4000
	v_mov_b32_e32 v5, v4
	s_branch .Lcvx_d2

.Lcvx_d2:
	global_load_dword v24, v[22:23], off nt
	v_lshl_add_u64 v[22:23], v[22:23], 0, s[26:27]
	global_load_dword v25, v[22:23], off nt
	v_lshl_add_u64 v[22:23], v[22:23], 0, s[26:27]
	global_load_dword v26, v[22:23], off nt
	v_lshl_add_u64 v[22:23], v[22:23], 0, s[26:27]
	global_load_dword v27, v[22:23], off nt
	v_lshl_add_u64 v[22:23], v[22:23], 0, s[26:27]
	global_load_dword v28, v[22:23], off nt
	v_lshl_add_u64 v[22:23], v[22:23], 0, s[26:27]
	global_load_dword v29, v[22:23], off nt
	v_lshl_add_u64 v[22:23], v[22:23], 0, s[26:27]
	global_load_dword v30, v[22:23], off nt
	v_lshl_add_u64 v[22:23], v[22:23], 0, s[26:27]
	global_load_dword v31, v[22:23], off nt
	v_lshl_add_u64 v[22:23], v[22:23], 0, s[26:27]
	global_load_dword v32, v[22:23], off nt
	v_lshl_add_u64 v[22:23], v[22:23], 0, s[26:27]
	global_load_dword v33, v[22:23], off nt
	v_lshl_add_u64 v[22:23], v[22:23], 0, s[26:27]
	global_load_dword v34, v[22:23], off nt
	v_lshl_add_u64 v[22:23], v[22:23], 0, s[26:27]
	global_load_dword v35, v[22:23], off nt
	v_lshl_add_u64 v[22:23], v[22:23], 0, s[26:27]
	global_load_dword v36, v[22:23], off nt
	v_lshl_add_u64 v[22:23], v[22:23], 0, s[26:27]
	global_load_dword v37, v[22:23], off nt
	v_lshl_add_u64 v[22:23], v[22:23], 0, s[26:27]
	global_load_dword v38, v[22:23], off nt
	v_lshl_add_u64 v[22:23], v[22:23], 0, s[26:27]
	global_load_dword v39, v[22:23], off nt
	v_lshl_add_u64 v[22:23], v[22:23], 0, s[26:27]
	global_load_dword v40, v[22:23], off nt
	v_lshl_add_u64 v[22:23], v[22:23], 0, s[26:27]
	global_load_dword v41, v[22:23], off nt
	v_lshl_add_u64 v[22:23], v[22:23], 0, s[26:27]
	global_load_dword v42, v[22:23], off nt
	v_lshl_add_u64 v[22:23], v[22:23], 0, s[26:27]
	global_load_dword v43, v[22:23], off nt
	v_lshl_add_u64 v[22:23], v[22:23], 0, s[26:27]
	global_load_dword v44, v[22:23], off nt
	v_lshl_add_u64 v[22:23], v[22:23], 0, s[26:27]
	global_load_dword v45, v[22:23], off nt
	v_lshl_add_u64 v[22:23], v[22:23], 0, s[26:27]
	global_load_dword v46, v[22:23], off nt
	v_lshl_add_u64 v[22:23], v[22:23], 0, s[26:27]
	global_load_dword v47, v[22:23], off nt
	v_lshl_add_u64 v[22:23], v[22:23], 0, s[26:27]
	global_load_dword v48, v[22:23], off nt
	v_lshl_add_u64 v[22:23], v[22:23], 0, s[26:27]
	global_load_dword v49, v[22:23], off nt
	v_lshl_add_u64 v[22:23], v[22:23], 0, s[26:27]
	global_load_dword v50, v[22:23], off nt
	v_lshl_add_u64 v[22:23], v[22:23], 0, s[26:27]
	global_load_dword v51, v[22:23], off nt
	v_lshl_add_u64 v[22:23], v[22:23], 0, s[26:27]
	global_load_dword v52, v[22:23], off nt
	v_lshl_add_u64 v[22:23], v[22:23], 0, s[26:27]
	global_load_dword v53, v[22:23], off nt
	v_lshl_add_u64 v[22:23], v[22:23], 0, s[26:27]
	global_load_dword v54, v[22:23], off nt
	v_lshl_add_u64 v[22:23], v[22:23], 0, s[26:27]
	global_load_dword v55, v[22:23], off nt
.Lcvx_noload:
	s_waitcnt lgkmcnt(0)
	ds_read2_b32 v[56:57], v21 offset0:0 offset1:8
	ds_read2_b32 v[58:59], v21 offset0:33 offset1:41
	ds_read2_b32 v[60:61], v21 offset0:66 offset1:74
	ds_read2_b32 v[62:63], v21 offset0:99 offset1:107
	ds_read2_b32 v[64:65], v21 offset0:132 offset1:140
	ds_read2_b32 v[66:67], v21 offset0:165 offset1:173
	ds_read2_b32 v[68:69], v21 offset0:198 offset1:206
	ds_read2_b32 v[70:71], v21 offset0:231 offset1:239
	ds_read2_b32 v[72:73], v21 offset0:16 offset1:24
	ds_read2_b32 v[74:75], v21 offset0:49 offset1:57
	ds_read2_b32 v[76:77], v21 offset0:82 offset1:90
	ds_read2_b32 v[78:79], v21 offset0:115 offset1:123
	ds_read2_b32 v[80:81], v21 offset0:148 offset1:156
	ds_read2_b32 v[82:83], v21 offset0:181 offset1:189
	ds_read2_b32 v[84:85], v21 offset0:214 offset1:222
	ds_read2_b32 v[86:87], v21 offset0:247 offset1:255
	s_waitcnt lgkmcnt(8)
	v_cvt_pk_bf16_f32 v88, v56, v58
	v_cvt_pk_bf16_f32 v89, v60, v62
	v_cvt_pk_bf16_f32 v90, v64, v66
	v_cvt_pk_bf16_f32 v91, v68, v70
	v_cvt_pk_bf16_f32 v92, v57, v59
	v_cvt_pk_bf16_f32 v93, v61, v63
	v_cvt_pk_bf16_f32 v94, v65, v67
	v_cvt_pk_bf16_f32 v95, v69, v71
	global_store_dwordx4 v6, v[88:91], s[20:21]
	s_add_u32 s20, s20, s15
	s_addc_u32 s21, s21, 0
	global_store_dwordx4 v6, v[92:95], s[20:21]
	s_add_u32 s20, s20, s15
	s_addc_u32 s21, s21, 0
	s_waitcnt lgkmcnt(0)
	v_cvt_pk_bf16_f32 v96, v72, v74
	v_cvt_pk_bf16_f32 v97, v76, v78
	v_cvt_pk_bf16_f32 v98, v80, v82
	v_cvt_pk_bf16_f32 v99, v84, v86
	v_cvt_pk_bf16_f32 v100, v73, v75
	v_cvt_pk_bf16_f32 v101, v77, v79
	v_cvt_pk_bf16_f32 v102, v81, v83
	v_cvt_pk_bf16_f32 v103, v85, v87
	global_store_dwordx4 v6, v[96:99], s[20:21]
	s_add_u32 s20, s20, s15
	s_addc_u32 s21, s21, 0
	global_store_dwordx4 v6, v[100:103], s[20:21]
	s_cmp_lt_u32 s4, s25
	s_cbranch_scc0 .Lcvx_done
	s_waitcnt vmcnt(4)
	s_branch .Lcvx_top
.Lcvx_done:
.LBB0_562:
	s_cmp_eq_u32 s80, 2
	v_readlane_b32 s7, v253, 43
	s_cselect_b64 s[0:1], -1, 0
	s_cmp_gt_i32 s7, 63
	s_cselect_b64 s[4:5], -1, 0
	s_and_b64 s[0:1], s[0:1], s[4:5]
	s_andn2_b64 vcc, exec, s[0:1]
	s_cbranch_vccnz .LBB0_584
	s_lshl_b32 s0, s7, 3
	v_readlane_b32 s4, v253, 45
	s_add_i32 s0, s0, s4
	s_add_i32 s6, s0, 0xfffffe00
	s_cmpk_gt_i32 s6, 0xaff
	v_readlane_b32 s5, v253, 46
	s_cbranch_scc1 .LBB0_584
	s_mov_b32 s4, s6
	s_movk_i32 s24, 0x600
	s_movk_i32 s25, 0xb00
	v_readlane_b32 s0, v253, 45
	s_mulk_i32 s0, 0x4200
	s_add_i32 s0, s97, s0
	v_readlane_b32 s22, v253, 41
	v_readlane_b32 s23, v253, 42
	v_readlane_b32 s6, v252, 1
	v_readlane_b32 s7, v252, 2
	s_load_dwordx4 s[8:11], s[6:7], 0x48
	s_load_dwordx2 s[14:15], s[6:7], 0x60
	v_lshlrev_b32_e32 v0, 1, v238
	v_and_b32_e32 v8, 3, v237
	v_and_or_b32 v8, v0, 24, v8
	v_lshrrev_b32_e32 v9, 2, v237
	v_and_or_b32 v9, v9, 4, v8
	v_lshlrev_b32_e32 v9, 2, v9
	v_lshrrev_b32_e32 v7, 5, v238
	v_lshrrev_b32_e32 v12, 3, v238
	v_lshlrev_b32_e32 v11, 3, v238
	v_and_b32_e32 v11, 56, v11
	v_lshlrev_b32_e32 v10, 1, v11
	v_lshl_add_u32 v4, v12, 11, v10
	v_and_b32_e32 v10, 31, v237
	v_lshlrev_b32_e32 v8, 2, v10
	v_mul_u32_u24_e32 v2, 0x84, v7
	v_add3_u32 v13, s0, v8, v2
	v_add_u32_e32 v14, 0x400, v13
	v_add_u32_e32 v15, 0x800, v13
	v_add_u32_e32 v16, 0xc00, v13
	v_add_u32_e32 v17, 0x1000, v13
	v_add_u32_e32 v18, 0x1400, v13
	v_add_u32_e32 v19, 0x1800, v13
	v_add_u32_e32 v20, 0x1c00, v13
	v_bfe_u32 v3, v10, 2, 1
	v_mul_u32_u24_e32 v3, 0x2100, v3
	v_lshrrev_b32_e32 v0, 3, v10
	v_lshlrev_b32_e32 v0, 2, v0
	v_and_b32_e32 v10, 3, v10
	v_or_b32_e32 v0, v0, v10
	v_lshlrev_b32_e32 v0, 2, v0
	v_add3_u32 v0, v0, v2, v3
	v_add_u32_e32 v144, s0, v0
	v_add_u32_e32 v145, 0x400, v144
	v_add_u32_e32 v146, 0x800, v144
	v_add_u32_e32 v147, 0xc00, v144
	v_add_u32_e32 v148, 0x1000, v144
	v_add_u32_e32 v149, 0x1400, v144
	v_add_u32_e32 v150, 0x1800, v144
	v_add_u32_e32 v151, 0x1c00, v144
	v_add_u32_e32 v152, 64, v144
	v_add_u32_e32 v153, 64, v145
	v_add_u32_e32 v154, 64, v146
	v_add_u32_e32 v155, 64, v147
	v_add_u32_e32 v156, 64, v148
	v_add_u32_e32 v157, 64, v149
	v_add_u32_e32 v158, 64, v150
	v_add_u32_e32 v159, 64, v151
	v_mul_u32_u24_e32 v10, 0x84, v11
	v_lshlrev_b32_e32 v2, 2, v12
	v_add3_u32 v21, s0, v10, v2
	v_mov_b32_e32 v11, v1
	s_waitcnt lgkmcnt(0)
	v_mul_u32_u24_e32 v10, 0x2c00, v7
	v_add_u32_e32 v10, v10, v8
	v_lshl_add_u64 v[136:137], s[8:9], 0, v[10:11]
	v_lshl_add_u64 v[138:139], s[10:11], 0, v[10:11]
	v_mul_u32_u24_e32 v10, 0x2400, v7
	v_add_u32_e32 v10, v10, v9
	v_lshl_add_u64 v[140:141], s[14:15], 0, v[10:11]
	s_cmpk_lt_u32 s4, 0xb00
	s_cbranch_scc0 .Lcvc_in1
	s_cmpk_gt_u32 s4, 0x57f
	s_cselect_b32 s5, 1, 0
	s_mul_i32 s6, s5, 0x580
	s_sub_i32 s6, s4, s6
	s_mul_i32 s7, s6, 0x2e9
	s_lshr_b32 s7, s7, 16
	s_mul_i32 s8, s7, 0x58
	s_sub_i32 s6, s6, s8
	s_lshr_b32 s8, s6, 2
	s_and_b32 s9, s6, 3
	s_lshl_b32 s10, s8, 9
	s_lshl_b32 s11, s9, 7
	s_add_i32 s10, s10, s11
	s_mul_i32 s11, s5, 0xb00000
	s_add_u32 s10, s10, s11
	s_add_u32 s10, s10, 0x1600000
	s_mul_i32 s11, s7, 0xb0000
	s_add_u32 s10, s10, s11
	s_mov_b32 s11, 0
	v_lshl_add_u64 v[22:23], v[136:137], 0, s[10:11]
	v_lshl_add_u64 v[142:143], v[138:139], 0, s[10:11]
	s_mov_b64 s[26:27], 0x5800
	s_lshl_b32 s8, s8, 3
	s_add_i32 s8, s8, s9
	s_mul_i32 s9, s5, 0xf80000
	s_lshl_b32 s8, s8, 16
	s_add_u32 s8, s8, s9
	s_lshl_b32 s9, s7, 7
	s_add_u32 s8, s8, s9
	s_add_u32 s8, s8, 0x3780000
	s_add_u32 s12, s22, s8
	s_addc_u32 s13, s23, 0
	s_mov_b32 s1, 1
	global_load_dword v24, v[22:23], off nt
	v_lshl_add_u64 v[22:23], v[22:23], 0, s[26:27]
	global_load_dword v25, v[22:23], off nt
	v_lshl_add_u64 v[22:23], v[22:23], 0, s[26:27]
	global_load_dword v26, v[22:23], off nt
	v_lshl_add_u64 v[22:23], v[22:23], 0, s[26:27]
	global_load_dword v27, v[22:23], off nt
	v_lshl_add_u64 v[22:23], v[22:23], 0, s[26:27]
	global_load_dword v28, v[22:23], off nt
	v_lshl_add_u64 v[22:23], v[22:23], 0, s[26:27]
	global_load_dword v29, v[22:23], off nt
	v_lshl_add_u64 v[22:23], v[22:23], 0, s[26:27]
	global_load_dword v30, v[22:23], off nt
	v_lshl_add_u64 v[22:23], v[22:23], 0, s[26:27]
	global_load_dword v31, v[22:23], off nt
	v_lshl_add_u64 v[22:23], v[22:23], 0, s[26:27]
	global_load_dword v32, v[22:23], off nt
	v_lshl_add_u64 v[22:23], v[22:23], 0, s[26:27]
	global_load_dword v33, v[22:23], off nt
	v_lshl_add_u64 v[22:23], v[22:23], 0, s[26:27]
	global_load_dword v34, v[22:23], off nt
	v_lshl_add_u64 v[22:23], v[22:23], 0, s[26:27]
	global_load_dword v35, v[22:23], off nt
	v_lshl_add_u64 v[22:23], v[22:23], 0, s[26:27]
	global_load_dword v36, v[22:23], off nt
	v_lshl_add_u64 v[22:23], v[22:23], 0, s[26:27]
	global_load_dword v37, v[22:23], off nt
	v_lshl_add_u64 v[22:23], v[22:23], 0, s[26:27]
	global_load_dword v38, v[22:23], off nt
	v_lshl_add_u64 v[22:23], v[22:23], 0, s[26:27]
	global_load_dword v39, v[22:23], off nt
	v_lshl_add_u64 v[22:23], v[22:23], 0, s[26:27]
	global_load_dword v40, v[22:23], off nt
	v_lshl_add_u64 v[22:23], v[22:23], 0, s[26:27]
	global_load_dword v41, v[22:23], off nt
	v_lshl_add_u64 v[22:23], v[22:23], 0, s[26:27]
	global_load_dword v42, v[22:23], off nt
	v_lshl_add_u64 v[22:23], v[22:23], 0, s[26:27]
	global_load_dword v43, v[22:23], off nt
	v_lshl_add_u64 v[22:23], v[22:23], 0, s[26:27]
	global_load_dword v44, v[22:23], off nt
	v_lshl_add_u64 v[22:23], v[22:23], 0, s[26:27]
	global_load_dword v45, v[22:23], off nt
	v_lshl_add_u64 v[22:23], v[22:23], 0, s[26:27]
	global_load_dword v46, v[22:23], off nt
	v_lshl_add_u64 v[22:23], v[22:23], 0, s[26:27]
	global_load_dword v47, v[22:23], off nt
	v_lshl_add_u64 v[22:23], v[22:23], 0, s[26:27]
	global_load_dword v48, v[22:23], off nt
	v_lshl_add_u64 v[22:23], v[22:23], 0, s[26:27]
	global_load_dword v49, v[22:23], off nt
	v_lshl_add_u64 v[22:23], v[22:23], 0, s[26:27]
	global_load_dword v50, v[22:23], off nt
	v_lshl_add_u64 v[22:23], v[22:23], 0, s[26:27]
	global_load_dword v51, v[22:23], off nt
	v_lshl_add_u64 v[22:23], v[22:23], 0, s[26:27]
	global_load_dword v52, v[22:23], off nt
	v_lshl_add_u64 v[22:23], v[22:23], 0, s[26:27]
	global_load_dword v53, v[22:23], off nt
	v_lshl_add_u64 v[22:23], v[22:23], 0, s[26:27]
	global_load_dword v54, v[22:23], off nt
	v_lshl_add_u64 v[22:23], v[22:23], 0, s[26:27]
	global_load_dword v55, v[22:23], off nt
	global_load_dword v56, v[142:143], off nt
	v_lshl_add_u64 v[142:143], v[142:143], 0, s[26:27]
	global_load_dword v57, v[142:143], off nt
	v_lshl_add_u64 v[142:143], v[142:143], 0, s[26:27]
	global_load_dword v58, v[142:143], off nt
	v_lshl_add_u64 v[142:143], v[142:143], 0, s[26:27]
	global_load_dword v59, v[142:143], off nt
	v_lshl_add_u64 v[142:143], v[142:143], 0, s[26:27]
	global_load_dword v60, v[142:143], off nt
	v_lshl_add_u64 v[142:143], v[142:143], 0, s[26:27]
	global_load_dword v61, v[142:143], off nt
	v_lshl_add_u64 v[142:143], v[142:143], 0, s[26:27]
	global_load_dword v62, v[142:143], off nt
	v_lshl_add_u64 v[142:143], v[142:143], 0, s[26:27]
	global_load_dword v63, v[142:143], off nt
	v_lshl_add_u64 v[142:143], v[142:143], 0, s[26:27]
	global_load_dword v64, v[142:143], off nt
	v_lshl_add_u64 v[142:143], v[142:143], 0, s[26:27]
	global_load_dword v65, v[142:143], off nt
	v_lshl_add_u64 v[142:143], v[142:143], 0, s[26:27]
	global_load_dword v66, v[142:143], off nt
	v_lshl_add_u64 v[142:143], v[142:143], 0, s[26:27]
	global_load_dword v67, v[142:143], off nt
	v_lshl_add_u64 v[142:143], v[142:143], 0, s[26:27]
	global_load_dword v68, v[142:143], off nt
	v_lshl_add_u64 v[142:143], v[142:143], 0, s[26:27]
	global_load_dword v69, v[142:143], off nt
	v_lshl_add_u64 v[142:143], v[142:143], 0, s[26:27]
	global_load_dword v70, v[142:143], off nt
	v_lshl_add_u64 v[142:143], v[142:143], 0, s[26:27]
	global_load_dword v71, v[142:143], off nt
	v_lshl_add_u64 v[142:143], v[142:143], 0, s[26:27]
	global_load_dword v72, v[142:143], off nt
	v_lshl_add_u64 v[142:143], v[142:143], 0, s[26:27]
	global_load_dword v73, v[142:143], off nt
	v_lshl_add_u64 v[142:143], v[142:143], 0, s[26:27]
	global_load_dword v74, v[142:143], off nt
	v_lshl_add_u64 v[142:143], v[142:143], 0, s[26:27]
	global_load_dword v75, v[142:143], off nt
	v_lshl_add_u64 v[142:143], v[142:143], 0, s[26:27]
	global_load_dword v76, v[142:143], off nt
	v_lshl_add_u64 v[142:143], v[142:143], 0, s[26:27]
	global_load_dword v77, v[142:143], off nt
	v_lshl_add_u64 v[142:143], v[142:143], 0, s[26:27]
	global_load_dword v78, v[142:143], off nt
	v_lshl_add_u64 v[142:143], v[142:143], 0, s[26:27]
	global_load_dword v79, v[142:143], off nt
	v_lshl_add_u64 v[142:143], v[142:143], 0, s[26:27]
	global_load_dword v80, v[142:143], off nt
	v_lshl_add_u64 v[142:143], v[142:143], 0, s[26:27]
	global_load_dword v81, v[142:143], off nt
	v_lshl_add_u64 v[142:143], v[142:143], 0, s[26:27]
	global_load_dword v82, v[142:143], off nt
	v_lshl_add_u64 v[142:143], v[142:143], 0, s[26:27]
	global_load_dword v83, v[142:143], off nt
	v_lshl_add_u64 v[142:143], v[142:143], 0, s[26:27]
	global_load_dword v84, v[142:143], off nt
	v_lshl_add_u64 v[142:143], v[142:143], 0, s[26:27]
	global_load_dword v85, v[142:143], off nt
	v_lshl_add_u64 v[142:143], v[142:143], 0, s[26:27]
	global_load_dword v86, v[142:143], off nt
	v_lshl_add_u64 v[142:143], v[142:143], 0, s[26:27]
	global_load_dword v87, v[142:143], off nt
	s_branch .Lcvc_e1
